# NSA2 selected loop: per-lane Q fragments kept in 32 registers instead of 8 LDS re-reads per tile step
# speedup vs baseline: 1.0005x; 1.0005x over previous
.Lnsa2_skipfill:
	v_readfirstlane_b32 s92, v200
	s_lshr_b32 s92, s92, 8
	s_and_b32 s92, s92, 1
	s_mul_i32 s93, s92, 0xb00
	s_add_i32 s93, s93, 0x1d000
	s_add_i32 s92, s93, 148
	s_add_i32 s94, s93, 276
	s_add_i32 s95, s93, 192
	s_add_i32 s96, s93, 320
	s_xor_b64 s[50:51], s[2:3], -1
	s_and_b64 s[0:1], s[2:3], exec
	s_cselect_b32 s61, s82, s80
	s_lshl_b32 s60, s61, 8
	v_and_b32_e32 v181, 0xc0, v2
	v_and_b32_e32 v151, 31, v2
	v_or_b32_e32 v182, s60, v181
	v_ashrrev_i32_e32 v3, 8, v2
	v_or_b32_e32 v0, v182, v151
	v_add_u32_e32 v185, s81, v3
	v_lshl_add_u64 v[146:147], s[34:35], 0, v[0:1]
	v_mad_u64_u32 v[4:5], s[0:1], v146, s73, v[138:139]
	v_lshlrev_b32_e32 v152, 6, v185
	v_bfe_u32 v186, v2, 5, 1
	v_mad_i32_i24 v5, v147, s73, v5
	v_ashrrev_i32_e32 v153, 31, v152
	v_ashrrev_i32_e32 v183, 3, v2
	v_lshl_add_u64 v[4:5], v[152:153], 1, v[4:5]
	v_lshlrev_b32_e32 v0, 4, v186
	v_med3_i32 v36, v183, 0, v141
	v_lshlrev_b32_e32 v38, 3, v2
	v_lshl_add_u64 v[24:25], v[4:5], 0, v[0:1]
	v_mul_u32_u24_e32 v36, 0x600, v36
	v_mov_b32_e32 v37, v1
	v_and_b32_e32 v150, 56, v38
	v_add_co_u32_e32 v28, vcc, s74, v24
	v_lshl_add_u64 v[36:37], v[36:37], 1, s[44:45]
	v_lshlrev_b32_e32 v44, 1, v150
	v_mov_b32_e32 v45, v1
	v_lshl_add_u64 v[32:33], v[24:25], 0, s[20:21]
	v_addc_co_u32_e32 v29, vcc, 0, v25, vcc
	v_lshl_add_u64 v[40:41], v[36:37], 0, v[44:45]
	global_load_dwordx4 v[4:7], v[24:25], off
	global_load_dwordx4 v[8:11], v[24:25], off offset:32
	global_load_dwordx4 v[12:15], v[32:33], off offset:32
	global_load_dwordx4 v[16:19], v[32:33], off offset:64
	global_load_dwordx4 v[20:23], v[24:25], off offset:64
	s_nop 0
	global_load_dwordx4 v[24:27], v[24:25], off offset:96
	s_nop 0
	global_load_dwordx4 v[28:31], v[28:29], off
	s_nop 0
	global_load_dwordx4 v[32:35], v[32:33], off offset:96
	s_nop 0
	global_load_dwordx4 v[36:39], v[40:41], off offset:1792
	s_nop 0
	global_load_dwordx4 v[40:43], v[40:41], off offset:1920
	v_or_b32_e32 v148, 32, v146
	v_mov_b32_e32 v149, v147
	v_lshl_add_u64 v[46:47], v[146:147], 2, s[18:19]
	v_lshl_add_u64 v[48:49], v[148:149], 2, s[18:19]
	global_load_dword v187, v[46:47], off
	global_load_dword v188, v[48:49], off
	v_lshlrev_b32_e32 v47, 7, v2
	v_and_b32_e32 v46, 63, v2
	v_lshlrev_b32_e32 v48, 4, v2
	v_mad_i32_i24 v175, v3, s72, 0
	v_and_b32_e32 v3, 0xffffe000, v47
	v_lshlrev_b32_e32 v46, 4, v46
	v_mul_lo_u32 v47, v183, s75
	v_and_b32_e32 v48, 0x70, v48
	v_add_u32_e32 v3, 0, v3
	v_and_b32_e32 v49, 16, v2
	v_lshrrev_b32_e32 v50, 2, v2
	v_mul_u32_u24_e32 v51, 0x90, v151
	v_add3_u32 v140, 0, v47, v48
	v_add_u32_e32 v176, v3, v46
	v_lshlrev_b32_e32 v184, 2, v186
	v_lshlrev_b32_e32 v3, 2, v2
	v_mad_u64_u32 v[142:143], s[0:1], v183, 48, v[140:141]
	v_add3_u32 v178, 0, v51, v0
	v_and_or_b32 v0, v50, 3, v184
	v_and_or_b32 v3, v3, 12, v49
	v_mul_u32_u24_e32 v0, 0xc0, v0
	v_lshlrev_b32_e32 v3, 1, v3
	v_add3_u32 v179, 0, v0, v3
	v_bitop3_b32 v0, v2, 31, v170 bitop3:0xe0
	s_lshl_b32 s84, s61, 2
	v_lshl_add_u64 v[144:145], s[44:45], 0, v[44:45]
	v_mad_u64_u32 v[154:155], s[0:1], v146, s73, 0
	v_sub_u32_e32 v192, v0, v184
	v_mov_b32_e32 v0, v1
	v_mov_b32_e32 v2, v1
	v_mov_b32_e32 v3, v1
	s_mov_b32 s85, 0
	s_add_i32 s83, s84, 4
	v_or_b32_e32 v143, 31, v182
	v_or_b32_e32 v177, 63, v182
	v_mad_i32_i24 v155, v147, s73, v155
	v_add_u32_e32 v190, 0xffffff41, v182
	v_add_u32_e32 v191, 0xffffff61, v182
	v_add_u32_e32 v180, 64, v183
	s_add_i32 s86, s60, 0x100
	v_mov_b32_e32 v193, 0xf149f2ca
	v_mov_b32_e32 v194, 0xf149f2ca
	s_mov_b32 s87, 0
	s_mov_b32 s0, 0
	v_mov_b64_e32 v[156:157], v[0:1]
	s_waitcnt vmcnt(11)
	ds_write_b128 v176, v[4:7] offset:53248
	s_waitcnt vmcnt(10)
	ds_write_b128 v176, v[8:11] offset:54272
	s_waitcnt vmcnt(7)
	ds_write_b128 v176, v[20:23] offset:55296
	s_waitcnt vmcnt(6)
	ds_write_b128 v176, v[24:27] offset:56320
	s_waitcnt vmcnt(5)
	ds_write_b128 v176, v[28:31] offset:57344
	ds_write_b128 v176, v[12:15] offset:58368
	ds_write_b128 v176, v[16:19] offset:59392
	s_waitcnt vmcnt(4)
	ds_write_b128 v176, v[32:35] offset:60416
	s_waitcnt lgkmcnt(0)
	s_barrier
	s_waitcnt vmcnt(3)
	ds_write_b128 v140, v[36:39]
	s_waitcnt vmcnt(2)
	ds_write_b128 v142, v[40:43] offset:18432
	s_waitcnt lgkmcnt(0)
	s_barrier
	ds_read_b128 v[218:221], v176 offset:53248
	ds_read_b128 v[222:225], v176 offset:54272
	ds_read_b128 v[226:229], v176 offset:55296
	ds_read_b128 v[230:233], v176 offset:56320
	ds_read_b128 v[234:237], v176 offset:57344
	ds_read_b128 v[242:245], v176 offset:58368
	ds_read_b128 v[246:249], v176 offset:59392
	ds_read_b128 v[250:253], v176 offset:60416
	s_waitcnt lgkmcnt(0)
	ds_read_b32 v189, v175 offset:43524
	v_mov_b32_e32 v16, v1
	v_mov_b32_e32 v17, v1
	v_mov_b32_e32 v4, v1
	v_mov_b32_e32 v5, v1
	v_mov_b32_e32 v6, v1
	v_mov_b32_e32 v7, v1
	v_mov_b32_e32 v8, v1
	v_mov_b32_e32 v9, v1
	v_mov_b32_e32 v10, v1
	v_mov_b32_e32 v11, v1
	v_mov_b32_e32 v12, v1
	v_mov_b32_e32 v13, v1
	v_mov_b32_e32 v14, v1
	v_mov_b32_e32 v15, v1
	v_mov_b64_e32 v[48:49], v[16:17]
	v_mov_b64_e32 v[64:65], v[16:17]
	v_mov_b64_e32 v[32:33], v[16:17]
	v_mov_b64_e32 v[46:47], v[14:15]
	v_mov_b64_e32 v[44:45], v[12:13]
	v_mov_b64_e32 v[42:43], v[10:11]
	v_mov_b64_e32 v[40:41], v[8:9]
	v_mov_b64_e32 v[38:39], v[6:7]
	v_mov_b64_e32 v[36:37], v[4:5]
	v_mov_b64_e32 v[34:35], v[2:3]
	v_mov_b64_e32 v[62:63], v[14:15]
	v_mov_b64_e32 v[60:61], v[12:13]
	v_mov_b64_e32 v[58:59], v[10:11]
	v_mov_b64_e32 v[56:57], v[8:9]
	v_mov_b64_e32 v[54:55], v[6:7]
	v_mov_b64_e32 v[52:53], v[4:5]
	v_mov_b64_e32 v[50:51], v[2:3]
	v_mov_b64_e32 v[30:31], v[14:15]
	v_mov_b64_e32 v[28:29], v[12:13]
	v_mov_b64_e32 v[26:27], v[10:11]
	v_mov_b64_e32 v[24:25], v[8:9]
	v_mov_b64_e32 v[22:23], v[6:7]
	v_mov_b64_e32 v[20:21], v[4:5]
	v_mov_b64_e32 v[18:19], v[2:3]

.LBB0_634:
	s_lshl_b32 s0, 1, s0
	s_waitcnt vmcnt(0)
	v_and_b32_e32 v0, s0, v187
	v_and_b32_e32 v66, s0, v188
	v_cmp_ne_u32_e64 s[6:7], 0, v0
	v_cmp_ne_u32_e32 vcc, 0, v66
	v_cmp_le_u32_e64 s[8:9], s85, v143
	v_cmp_le_u32_e64 s[2:3], s85, v177
	s_and_b64 s[8:9], s[8:9], s[6:7]
	s_and_b64 s[2:3], s[2:3], vcc
	s_cmp_lg_u64 s[8:9], 0
	s_cselect_b64 s[8:9], -1, 0
	s_cmp_lg_u64 s[2:3], 0
	s_cselect_b64 s[2:3], -1, 0
	v_cndmask_b32_e64 v0, 0, 1, s[8:9]
	v_cndmask_b32_e64 v167, 0, 1, s[2:3]
	s_or_b64 s[0:1], s[8:9], s[2:3]
	s_and_saveexec_b64 s[54:55], s[0:1]
	s_cbranch_execz .LBB0_646
	s_cmp_eq_u32 s87, 0
	s_cselect_b64 s[58:59], -1, 0
	s_and_b64 s[0:1], s[58:59], exec
	s_cselect_b32 s0, 0, 0x2400
	v_add_u32_e32 v168, s0, v178
	ds_read_b128 v[158:161], v168
	v_cmp_gt_i32_e64 s[4:5], s85, v190
	s_waitcnt lgkmcnt(1)
	v_cndmask_b32_e64 v66, v173, v189, s[6:7]
	ds_read_b128 v[196:199], v168 offset:32
	v_cndmask_b32_e64 v166, 0, v171, s[4:5]
	v_cndmask_b32_e64 v66, v66, 0, s[4:5]
	v_cndmask_b32_e32 v67, v173, v189, vcc
	v_cmp_gt_i32_e64 s[4:5], s85, v191
	v_cndmask_b32_e64 v240, v173, v66, s[8:9]
	s_nop 0
	v_cndmask_b32_e64 v67, v67, 0, s[4:5]
	s_nop 1
	v_cndmask_b32_e64 v241, v173, v67, s[2:3]
	s_waitcnt lgkmcnt(1)
	v_mfma_f32_32x32x16_bf16 v[98:113], v[158:161], v[218:221], 0
	s_waitcnt lgkmcnt(0)
	v_mfma_f32_32x32x16_bf16 v[114:129], v[158:161], v[234:237], 0
	ds_read_b128 v[158:161], v168 offset:4608
	ds_read_b128 v[214:217], v168 offset:4640
	s_waitcnt lgkmcnt(1)
	v_mfma_f32_32x32x16_bf16 v[82:97], v[158:161], v[218:221], 0
	v_mfma_f32_32x32x16_bf16 v[66:81], v[158:161], v[234:237], 0
	v_mfma_f32_32x32x16_bf16 v[98:113], v[196:199], v[222:225], v[98:113]
	v_mfma_f32_32x32x16_bf16 v[114:129], v[196:199], v[242:245], v[114:129]
	ds_read_b128 v[158:161], v168 offset:64
	ds_read_b128 v[196:199], v168 offset:96
	s_waitcnt lgkmcnt(2)
	v_mfma_f32_32x32x16_bf16 v[82:97], v[214:217], v[222:225], v[82:97]
	v_mfma_f32_32x32x16_bf16 v[66:81], v[214:217], v[242:245], v[66:81]
	s_waitcnt lgkmcnt(1)
	v_mfma_f32_32x32x16_bf16 v[98:113], v[158:161], v[226:229], v[98:113]
	s_waitcnt lgkmcnt(0)
	v_mfma_f32_32x32x16_bf16 v[114:129], v[158:161], v[246:249], v[114:129]
	ds_read_b128 v[158:161], v168 offset:4672
	ds_read_b128 v[214:217], v168 offset:4704
	s_waitcnt lgkmcnt(1)
	v_mfma_f32_32x32x16_bf16 v[82:97], v[158:161], v[226:229], v[82:97]
	v_mfma_f32_32x32x16_bf16 v[66:81], v[158:161], v[246:249], v[66:81]
	v_cndmask_b32_e64 v158, 0, v172, s[6:7]
	v_or3_b32 v0, v158, v166, v0
	v_cndmask_b32_e64 v158, v158, v0, s[8:9]
	v_and_b32_e32 v0, 0x100, v158
	v_cmp_ne_u32_e64 s[6:7], 0, v0
	v_add_u32_e32 v0, s60, v192
	v_mfma_f32_32x32x16_bf16 v[98:113], v[196:199], v[230:233], v[98:113]
	v_mfma_f32_32x32x16_bf16 v[114:129], v[196:199], v[250:253], v[114:129]
	s_waitcnt lgkmcnt(0)
	v_mfma_f32_32x32x16_bf16 v[82:97], v[214:217], v[230:233], v[82:97]
	v_mfma_f32_32x32x16_bf16 v[66:81], v[214:217], v[250:253], v[66:81]
	s_and_saveexec_b64 s[8:9], s[6:7]
	s_cbranch_execz .LBB0_641
	v_lshl_add_u32 v206, v0, 2, s92
	v_and_b32_e32 v205, 0x10000, v158
	v_cmp_ne_u32_e64 s[6:7], 0, v205
	v_mov_b32_e32 v207, s93
	s_nop 1
	v_cndmask_b32_e64 v206, v207, v206, s[6:7]
	ds_read2_b32 v[208:209], v206 offset0:59 offset1:58
	ds_read2_b32 v[210:211], v206 offset0:57 offset1:56
	ds_read2_b32 v[212:213], v206 offset0:51 offset1:50
	ds_read2_b32 v[214:215], v206 offset0:49 offset1:48
	ds_read2_b32 v[216:217], v206 offset0:43 offset1:42
	ds_read2_b32 v[218:219], v206 offset0:41 offset1:40
	ds_read2_b32 v[220:221], v206 offset0:35 offset1:34
	ds_read2_b32 v[222:223], v206 offset0:33 offset1:32
	ds_read2_b32 v[224:225], v206 offset0:27 offset1:26
	ds_read2_b32 v[226:227], v206 offset0:25 offset1:24
	ds_read2_b32 v[228:229], v206 offset0:19 offset1:18
	ds_read2_b32 v[230:231], v206 offset0:17 offset1:16
	ds_read2_b32 v[232:233], v206 offset0:11 offset1:10
	ds_read2_b32 v[234:235], v206 offset0:9 offset1:8
	ds_read2_b32 v[236:237], v206 offset0:3 offset1:2
	ds_read2_b32 v[238:239], v206 offset0:1 offset1:0
	s_waitcnt lgkmcnt(8)
	v_pk_add_f32 v[98:99], v[98:99], v[208:209]
	v_pk_add_f32 v[100:101], v[100:101], v[210:211]
	v_pk_add_f32 v[102:103], v[102:103], v[212:213]
	v_pk_add_f32 v[104:105], v[104:105], v[214:215]
	v_pk_add_f32 v[106:107], v[106:107], v[216:217]
	v_pk_add_f32 v[108:109], v[108:109], v[218:219]
	v_pk_add_f32 v[110:111], v[110:111], v[220:221]
	v_pk_add_f32 v[112:113], v[112:113], v[222:223]
	s_waitcnt lgkmcnt(0)
	v_pk_add_f32 v[82:83], v[82:83], v[224:225]
	v_pk_add_f32 v[84:85], v[84:85], v[226:227]
	v_pk_add_f32 v[86:87], v[86:87], v[228:229]
	v_pk_add_f32 v[88:89], v[88:89], v[230:231]
	v_pk_add_f32 v[90:91], v[90:91], v[232:233]
	v_pk_add_f32 v[92:93], v[92:93], v[234:235]
	v_pk_add_f32 v[94:95], v[94:95], v[236:237]
	v_pk_add_f32 v[96:97], v[96:97], v[238:239]
	ds_read_b128 v[218:221], v176 offset:53248
	ds_read_b128 v[222:225], v176 offset:54272
	ds_read_b128 v[226:229], v176 offset:55296
	ds_read_b128 v[230:233], v176 offset:56320
	ds_read_b128 v[234:237], v176 offset:57344
.LBB0_641:
	s_or_b64 exec, exec, s[8:9]
	v_cndmask_b32_e32 v158, 0, v172, vcc
	v_cndmask_b32_e64 v159, 0, v171, s[4:5]
	v_or3_b32 v159, v158, v159, v167
	v_cndmask_b32_e64 v158, v158, v159, s[2:3]
	v_and_b32_e32 v159, 0x100, v158
	v_cmp_ne_u32_e32 vcc, 0, v159
	s_and_saveexec_b64 s[2:3], vcc
	s_cbranch_execz .LBB0_643
	v_lshl_add_u32 v206, v0, 2, s94
	v_and_b32_e32 v205, 0x10000, v158
	v_cmp_ne_u32_e32 vcc, 0, v205
	v_mov_b32_e32 v207, s93
	s_nop 1
	v_cndmask_b32_e32 v206, v207, v206, vcc
	ds_read2_b32 v[208:209], v206 offset0:59 offset1:58
	ds_read2_b32 v[210:211], v206 offset0:57 offset1:56
	ds_read2_b32 v[212:213], v206 offset0:51 offset1:50
	ds_read2_b32 v[214:215], v206 offset0:49 offset1:48
	ds_read2_b32 v[216:217], v206 offset0:43 offset1:42
	ds_read2_b32 v[218:219], v206 offset0:41 offset1:40
	ds_read2_b32 v[220:221], v206 offset0:35 offset1:34
	ds_read2_b32 v[222:223], v206 offset0:33 offset1:32
	ds_read2_b32 v[224:225], v206 offset0:27 offset1:26
	ds_read2_b32 v[226:227], v206 offset0:25 offset1:24
	ds_read2_b32 v[228:229], v206 offset0:19 offset1:18
	ds_read2_b32 v[230:231], v206 offset0:17 offset1:16
	ds_read2_b32 v[232:233], v206 offset0:11 offset1:10
	ds_read2_b32 v[234:235], v206 offset0:9 offset1:8
	ds_read2_b32 v[236:237], v206 offset0:3 offset1:2
	ds_read2_b32 v[238:239], v206 offset0:1 offset1:0
	s_waitcnt lgkmcnt(8)
	v_pk_add_f32 v[114:115], v[114:115], v[208:209]
	v_pk_add_f32 v[116:117], v[116:117], v[210:211]
	v_pk_add_f32 v[118:119], v[118:119], v[212:213]
	v_pk_add_f32 v[120:121], v[120:121], v[214:215]
	v_pk_add_f32 v[122:123], v[122:123], v[216:217]
	v_pk_add_f32 v[124:125], v[124:125], v[218:219]
	v_pk_add_f32 v[126:127], v[126:127], v[220:221]
	v_pk_add_f32 v[128:129], v[128:129], v[222:223]
	s_waitcnt lgkmcnt(0)
	v_pk_add_f32 v[66:67], v[66:67], v[224:225]
	v_pk_add_f32 v[68:69], v[68:69], v[226:227]
	v_pk_add_f32 v[70:71], v[70:71], v[228:229]
	v_pk_add_f32 v[72:73], v[72:73], v[230:231]
	v_pk_add_f32 v[74:75], v[74:75], v[232:233]
	v_pk_add_f32 v[76:77], v[76:77], v[234:235]
	v_pk_add_f32 v[78:79], v[78:79], v[236:237]
	v_pk_add_f32 v[80:81], v[80:81], v[238:239]
	ds_read_b128 v[218:221], v176 offset:53248
	ds_read_b128 v[222:225], v176 offset:54272
	ds_read_b128 v[226:229], v176 offset:55296
	ds_read_b128 v[230:233], v176 offset:56320
	ds_read_b128 v[234:237], v176 offset:57344
